# P8: inside the peeled first load section the 16 LDS reads issue first, unit head and scalar chain behind them (loop body untouched)
# baseline (speedup 1.0000x reference)
.Lpeel8_1768:
	s_add_u32 s48, s28, 0xfffc0080
	s_addc_u32 s49, s29, -1
	s_and_b64 s[46:47], s[30:31], exec
	s_cselect_b32 s49, s23, s49
	s_cselect_b32 s48, s56, s48
	s_cselect_b32 s47, s57, s60
	s_cselect_b32 s46, s58, s59
	s_add_i32 m0, s40, 0xc000
	s_nop 0
	global_load_lds_dwordx4 v206, s[28:29]
	s_add_i32 m0, s40, 0xe000
	s_nop 0
	global_load_lds_dwordx4 v208, s[28:29]
	s_waitcnt vmcnt(8) lgkmcnt(0)
	s_barrier
	v_mfma_f32_16x16x32_bf16 v[130:133], v[134:137], v[166:169], 0
	v_mfma_f32_16x16x32_bf16 v[122:125], v[142:145], v[166:169], 0
	v_mfma_f32_16x16x32_bf16 v[114:117], v[134:137], v[174:177], 0
	v_mfma_f32_16x16x32_bf16 v[106:109], v[142:145], v[174:177], 0
	v_mfma_f32_16x16x32_bf16 v[98:101], v[134:137], v[182:185], 0
	v_mfma_f32_16x16x32_bf16 v[90:93], v[142:145], v[182:185], 0
	v_mfma_f32_16x16x32_bf16 v[82:85], v[134:137], v[190:193], 0
	v_mfma_f32_16x16x32_bf16 v[74:77], v[142:145], v[190:193], 0
	v_mfma_f32_16x16x32_bf16 v[130:133], v[138:141], v[170:173], v[130:133]
	v_mfma_f32_16x16x32_bf16 v[122:125], v[146:149], v[170:173], v[122:125]
	v_mfma_f32_16x16x32_bf16 v[114:117], v[138:141], v[178:181], v[114:117]
	v_mfma_f32_16x16x32_bf16 v[106:109], v[146:149], v[178:181], v[106:109]
	v_mfma_f32_16x16x32_bf16 v[98:101], v[138:141], v[186:189], v[98:101]
	v_mfma_f32_16x16x32_bf16 v[90:93], v[146:149], v[186:189], v[90:93]
	v_mfma_f32_16x16x32_bf16 v[82:85], v[138:141], v[194:197], v[82:85]
	v_mfma_f32_16x16x32_bf16 v[74:77], v[146:149], v[194:197], v[74:77]
	v_mfma_f32_16x16x32_bf16 v[126:129], v[150:153], v[166:169], 0
	v_mfma_f32_16x16x32_bf16 v[118:121], v[158:161], v[166:169], 0
	v_mfma_f32_16x16x32_bf16 v[110:113], v[150:153], v[174:177], 0
	v_mfma_f32_16x16x32_bf16 v[102:105], v[158:161], v[174:177], 0
	v_mfma_f32_16x16x32_bf16 v[94:97], v[150:153], v[182:185], 0
	v_mfma_f32_16x16x32_bf16 v[86:89], v[158:161], v[182:185], 0
	v_mfma_f32_16x16x32_bf16 v[78:81], v[150:153], v[190:193], 0
	v_mfma_f32_16x16x32_bf16 v[70:73], v[158:161], v[190:193], 0
	v_mfma_f32_16x16x32_bf16 v[126:129], v[154:157], v[170:173], v[126:129]
	v_mfma_f32_16x16x32_bf16 v[118:121], v[162:165], v[170:173], v[118:121]
	v_mfma_f32_16x16x32_bf16 v[110:113], v[154:157], v[178:181], v[110:113]
	v_mfma_f32_16x16x32_bf16 v[102:105], v[162:165], v[178:181], v[102:105]
	v_mfma_f32_16x16x32_bf16 v[94:97], v[154:157], v[186:189], v[94:97]
	v_mfma_f32_16x16x32_bf16 v[86:89], v[162:165], v[186:189], v[86:89]
	v_mfma_f32_16x16x32_bf16 v[78:81], v[154:157], v[194:197], v[78:81]
	v_mfma_f32_16x16x32_bf16 v[70:73], v[162:165], v[194:197], v[70:73]
	s_barrier
	s_add_i32 s62, s53, s12
	s_add_u32 s98, s46, s16
	s_addc_u32 s99, s47, s17
	s_mov_b32 m0, s62
	ds_read_b128 v[166:169], v220 offset:16384
	ds_read_b128 v[170:173], v220 offset:17408
	ds_read_b128 v[174:177], v220 offset:18432
	ds_read_b128 v[178:181], v220 offset:19456
	ds_read_b128 v[182:185], v220 offset:20480
	ds_read_b128 v[186:189], v220 offset:21504
	ds_read_b128 v[190:193], v220 offset:22528
	ds_read_b128 v[194:197], v220 offset:23552
	global_load_lds_dwordx4 v202, s[46:47]
	s_add_i32 m0, s62, 0x2000
	s_add_u32 s62, s46, 0x40000
	s_addc_u32 s63, s47, 0
	s_add_i32 s64, s54, s12
	global_load_lds_dwordx4 v198, s[46:47]
	s_mov_b32 m0, s64
	s_nop 0
	global_load_lds_dwordx4 v202, s[62:63]
	s_add_i32 m0, s64, 0x2000
	s_nop 0
	global_load_lds_dwordx4 v198, s[62:63]
	s_add_u32 s100, s48, s16
	s_addc_u32 s101, s49, s17
	s_mov_b32 m0, s40
	s_nop 0
	global_load_lds_dwordx4 v204, s[48:49]
	s_mov_b32 m0, s41
	s_nop 0
	global_load_lds_dwordx4 v200, s[48:49]
	s_waitcnt vmcnt(8) lgkmcnt(0)
	s_barrier
	v_mfma_f32_16x16x32_bf16 v[66:69], v[134:137], v[166:169], 0
	v_mfma_f32_16x16x32_bf16 v[58:61], v[142:145], v[166:169], 0
	v_mfma_f32_16x16x32_bf16 v[50:53], v[134:137], v[174:177], 0
	v_mfma_f32_16x16x32_bf16 v[42:45], v[142:145], v[174:177], 0
	v_mfma_f32_16x16x32_bf16 v[34:37], v[134:137], v[182:185], 0
	v_mfma_f32_16x16x32_bf16 v[26:29], v[142:145], v[182:185], 0
	v_mfma_f32_16x16x32_bf16 v[18:21], v[134:137], v[190:193], 0
	v_mfma_f32_16x16x32_bf16 v[10:13], v[142:145], v[190:193], 0
	v_mfma_f32_16x16x32_bf16 v[66:69], v[138:141], v[170:173], v[66:69]
	v_mfma_f32_16x16x32_bf16 v[58:61], v[146:149], v[170:173], v[58:61]
	v_mfma_f32_16x16x32_bf16 v[50:53], v[138:141], v[178:181], v[50:53]
	v_mfma_f32_16x16x32_bf16 v[42:45], v[146:149], v[178:181], v[42:45]
	v_mfma_f32_16x16x32_bf16 v[34:37], v[138:141], v[186:189], v[34:37]
	v_mfma_f32_16x16x32_bf16 v[26:29], v[146:149], v[186:189], v[26:29]
	v_mfma_f32_16x16x32_bf16 v[18:21], v[138:141], v[194:197], v[18:21]
	v_mfma_f32_16x16x32_bf16 v[10:13], v[146:149], v[194:197], v[10:13]
	v_mfma_f32_16x16x32_bf16 v[62:65], v[150:153], v[166:169], 0
	v_mfma_f32_16x16x32_bf16 v[54:57], v[158:161], v[166:169], 0
	v_mfma_f32_16x16x32_bf16 v[46:49], v[150:153], v[174:177], 0
	v_mfma_f32_16x16x32_bf16 v[38:41], v[158:161], v[174:177], 0
	v_mfma_f32_16x16x32_bf16 v[30:33], v[150:153], v[182:185], 0
	v_mfma_f32_16x16x32_bf16 v[22:25], v[158:161], v[182:185], 0
	v_mfma_f32_16x16x32_bf16 v[14:17], v[150:153], v[190:193], 0
	v_mfma_f32_16x16x32_bf16 v[6:9], v[158:161], v[190:193], 0
	v_mfma_f32_16x16x32_bf16 v[62:65], v[154:157], v[170:173], v[62:65]
	v_mfma_f32_16x16x32_bf16 v[54:57], v[162:165], v[170:173], v[54:57]
	v_mfma_f32_16x16x32_bf16 v[46:49], v[154:157], v[178:181], v[46:49]
	v_mfma_f32_16x16x32_bf16 v[38:41], v[162:165], v[178:181], v[38:41]
	v_mfma_f32_16x16x32_bf16 v[30:33], v[154:157], v[186:189], v[30:33]
	v_mfma_f32_16x16x32_bf16 v[22:25], v[162:165], v[186:189], v[22:25]
	v_mfma_f32_16x16x32_bf16 v[14:17], v[154:157], v[194:197], v[14:17]
	v_mfma_f32_16x16x32_bf16 v[6:9], v[162:165], v[194:197], v[6:9]
	s_barrier
	s_branch .Lpeel8_p3
